# H + attention loop trims + first-tile K fragment reads issued right after the pair barrier (LDS latency under the DMA issue block)
# baseline (speedup 1.0000x reference)
.LBB0_3759:
	s_add_i32 s50, s51, 2
	s_cmp_ge_u32 s50, s48
	s_cselect_b64 s[22:23], -1, 0
	v_xor_b32_e32 v200, 0x8000, v200
	v_xor_b32_e32 v157, 0x8000, v157
	s_xor_b32 s74, s74, 0x8000
	s_add_i32 s70, s74, s75
	s_waitcnt vmcnt(0) lgkmcnt(0)
	s_barrier
	ds_read_b128 v[6:9], v200
	ds_read_b128 v[10:13], v200 offset:512
	s_and_b64 vcc, exec, s[22:23]
	s_cbranch_vccnz .LBB0_3761
	global_load_dwordx4 v[2:5], v[196:197], off
.LBB0_3761:
	s_add_i32 s0, s51, 2
	s_sub_i32 s1, s0, s48
	s_min_u32 s2, s0, s1
	s_lshl_b64 s[0:1], s[2:3], 13
	v_lshl_add_u64 v[14:15], v[180:181], 0, s[0:1]
	v_lshl_add_u64 v[218:219], v[182:183], 0, s[0:1]
	s_mov_b32 m0, s70
	s_nop 0
	global_load_lds_dwordx4 v[14:15], off
	s_add_i32 m0, s70, 0x2000
	s_nop 0
	global_load_lds_dwordx4 v[218:219], off
	s_add_i32 s0, s51, 3
	s_sub_i32 s1, s0, s48
	s_min_u32 s2, s0, s1
	s_lshl_b64 s[0:1], s[2:3], 13
	v_lshl_add_u64 v[14:15], v[180:181], 0, s[0:1]
	v_lshl_add_u64 v[218:219], v[182:183], 0, s[0:1]
	s_add_i32 m0, s70, 0x4000
	s_nop 0
	global_load_lds_dwordx4 v[14:15], off
	s_add_i32 m0, s70, 0x6000
	s_nop 0
	global_load_lds_dwordx4 v[218:219], off
	s_cmp_gt_u32 s51, s47
	s_cbranch_scc1 .LBB0_3765
	v_lshrrev_b32_e32 v1, v160, v152
	v_lshrrev_b32_e32 v14, v160, v153
	v_bitop3_b32 v228, v1, s27, v1 bitop3:0xc
	v_bitop3_b32 v229, v1, s28, v1 bitop3:0xc
	v_bitop3_b32 v230, v1, s29, v1 bitop3:0xc
	v_bitop3_b32 v231, v1, s30, v1 bitop3:0xc
	s_waitcnt lgkmcnt(1)
	v_mfma_f32_32x32x16_bf16 v[80:95], v[6:9], v[144:147], v[64:79]
	v_mul_u32_u24_e32 v228, 0xf000, v228
	v_mul_u32_u24_e32 v229, 0x7800, v229
	v_mul_u32_u24_e32 v230, 0x3c00, v230
	v_mul_u32_u24_e32 v231, 0x1e00, v231
	s_waitcnt lgkmcnt(0)
	v_mfma_f32_32x32x16_bf16 v[96:111], v[10:13], v[144:147], v[64:79]
	ds_read_b128 v[6:9], v200 offset:2048
	ds_read_b128 v[10:13], v200 offset:2560
	v_bitop3_b32 v232, v14, s27, v14 bitop3:0xc
	v_bitop3_b32 v233, v14, s28, v14 bitop3:0xc
	v_bitop3_b32 v234, v14, s29, v14 bitop3:0xc
	v_bitop3_b32 v235, v14, s30, v14 bitop3:0xc
	v_mul_u32_u24_e32 v232, 0xf000, v232
	v_mul_u32_u24_e32 v233, 0x7800, v233
	v_mul_u32_u24_e32 v234, 0x3c00, v234
	v_mul_u32_u24_e32 v235, 0x1e00, v235
	s_waitcnt lgkmcnt(1)
	v_mfma_f32_32x32x16_bf16 v[80:95], v[6:9], v[136:139], v[80:95]
	v_bitop3_b32 v236, v1, s31, v1 bitop3:0xc
	v_bitop3_b32 v237, v1, s33, v1 bitop3:0xc
	v_bitop3_b32 v238, v1, s34, v1 bitop3:0xc
	v_bitop3_b32 v239, v1, s35, v1 bitop3:0xc
	s_waitcnt lgkmcnt(0)
	v_mfma_f32_32x32x16_bf16 v[96:111], v[10:13], v[136:139], v[96:111]
	ds_read_b128 v[6:9], v200 offset:4096
	ds_read_b128 v[10:13], v200 offset:4608
	v_mul_u32_u24_e32 v236, 0xf00, v236
	v_mul_u32_u24_e32 v237, 0x780, v237
	v_mul_u32_u24_e32 v238, 0x3c0, v238
	v_mul_u32_u24_e32 v239, 0x1e0, v239
	v_bitop3_b32 v224, v14, s31, v14 bitop3:0xc
	v_bitop3_b32 v225, v14, s33, v14 bitop3:0xc
	v_bitop3_b32 v226, v14, s34, v14 bitop3:0xc
	v_bitop3_b32 v227, v14, s35, v14 bitop3:0xc
	s_waitcnt lgkmcnt(1)
	v_mfma_f32_32x32x16_bf16 v[80:95], v[6:9], v[140:143], v[80:95]
	v_mul_u32_u24_e32 v224, 0xf00, v224
	v_mul_u32_u24_e32 v225, 0x780, v225
	v_mul_u32_u24_e32 v226, 0x3c0, v226
	v_mul_u32_u24_e32 v227, 0x1e0, v227
	s_waitcnt lgkmcnt(0)
	v_mfma_f32_32x32x16_bf16 v[96:111], v[10:13], v[140:143], v[96:111]
	ds_read_b128 v[6:9], v200 offset:6144
	ds_read_b128 v[10:13], v200 offset:6656
	s_xor_b64 s[4:5], s[20:21], -1
	s_waitcnt lgkmcnt(1)
	v_mfma_f32_32x32x16_bf16 v[80:95], v[6:9], v[148:151], v[80:95]
	s_waitcnt lgkmcnt(0)
	v_mfma_f32_32x32x16_bf16 v[96:111], v[10:13], v[148:151], v[96:111]
	v_mfma_f32_32x32x16_bf16 v[80:95], v[112:115], v[228:231], v[80:95]
	v_mfma_f32_32x32x16_bf16 v[96:111], v[112:115], v[232:235], v[96:111]
	v_mfma_f32_32x32x16_bf16 v[80:95], v[116:119], v[236:239], v[80:95]
	v_mfma_f32_32x32x16_bf16 v[96:111], v[116:119], v[224:227], v[96:111]
	s_nop 15
	s_nop 7
	v_max3_f32 v1, v80, v81, v82
	v_max3_f32 v6, v83, v84, v85
	v_max3_f32 v1, v1, v86, v87
	v_max3_f32 v6, v6, v88, v89
	v_max3_f32 v1, v1, v90, v91
	v_max3_f32 v6, v6, v92, v93
	v_max3_f32 v1, v1, v94, v95
	v_max_f32 v1, v1, v6
	s_nop 0
	v_max3_f32 v7, v96, v97, v98
	v_max3_f32 v6, v99, v100, v101
	v_max3_f32 v7, v7, v102, v103
	v_max3_f32 v6, v6, v104, v105
	v_max3_f32 v7, v7, v106, v107
	v_max3_f32 v6, v6, v108, v109
	v_max3_f32 v7, v7, v110, v111
	v_max3_f32 v7, v7, v6, v1
	s_nop 0
	v_mov_b32_e32 v1, v7
	s_nop 1
	v_permlane32_swap_b32_e32 v7, v1
	v_max_f32_e32 v1, v7, v1
	v_cmp_lt_f32_e64 s[0:1], s36, v1
	s_and_b64 s[10:11], s[0:1], s[4:5]
	v_cmp_lt_f32_e32 vcc, s37, v1
	s_or_b64 s[4:5], vcc, s[10:11]
	s_and_b64 vcc, exec, s[4:5]
	s_cbranch_vccz .LBB0_3764
	v_cndmask_b32_e64 v6, 0, v1, s[4:5]
	v_exp_f32_e64 v1, -v6
	v_add_f32_e32 v171, v171, v6
	s_or_b64 s[0:1], s[20:21], s[0:1]
	v_xor_b32_e32 v64, 0x80000000, v171
	v_cndmask_b32_e64 v8, v1, 1.0, s[10:11]
	s_andn2_b64 s[4:5], s[20:21], exec
	s_and_b64 s[0:1], s[0:1], exec
	v_pk_add_f32 v[80:81], v[80:81], v[6:7] op_sel_hi:[1,0] neg_lo:[0,1] neg_hi:[0,1]
	v_pk_add_f32 v[96:97], v[96:97], v[6:7] op_sel_hi:[1,0] neg_lo:[0,1] neg_hi:[0,1]
	v_pk_add_f32 v[82:83], v[82:83], v[6:7] op_sel_hi:[1,0] neg_lo:[0,1] neg_hi:[0,1]
	v_pk_add_f32 v[98:99], v[98:99], v[6:7] op_sel_hi:[1,0] neg_lo:[0,1] neg_hi:[0,1]
	v_pk_add_f32 v[84:85], v[84:85], v[6:7] op_sel_hi:[1,0] neg_lo:[0,1] neg_hi:[0,1]
	v_pk_add_f32 v[100:101], v[100:101], v[6:7] op_sel_hi:[1,0] neg_lo:[0,1] neg_hi:[0,1]
	v_pk_add_f32 v[86:87], v[86:87], v[6:7] op_sel_hi:[1,0] neg_lo:[0,1] neg_hi:[0,1]
	v_pk_add_f32 v[102:103], v[102:103], v[6:7] op_sel_hi:[1,0] neg_lo:[0,1] neg_hi:[0,1]
	v_pk_add_f32 v[88:89], v[88:89], v[6:7] op_sel_hi:[1,0] neg_lo:[0,1] neg_hi:[0,1]
	v_pk_add_f32 v[104:105], v[104:105], v[6:7] op_sel_hi:[1,0] neg_lo:[0,1] neg_hi:[0,1]
	v_pk_add_f32 v[90:91], v[90:91], v[6:7] op_sel_hi:[1,0] neg_lo:[0,1] neg_hi:[0,1]
	v_pk_add_f32 v[106:107], v[106:107], v[6:7] op_sel_hi:[1,0] neg_lo:[0,1] neg_hi:[0,1]
	v_pk_add_f32 v[92:93], v[92:93], v[6:7] op_sel_hi:[1,0] neg_lo:[0,1] neg_hi:[0,1]
	v_pk_add_f32 v[108:109], v[108:109], v[6:7] op_sel_hi:[1,0] neg_lo:[0,1] neg_hi:[0,1]
	v_pk_add_f32 v[94:95], v[94:95], v[6:7] op_sel_hi:[1,0] neg_lo:[0,1] neg_hi:[0,1]
	v_pk_add_f32 v[110:111], v[110:111], v[6:7] op_sel_hi:[1,0] neg_lo:[0,1] neg_hi:[0,1]
	v_mov_b32_e32 v65, v64
	v_mov_b32_e32 v66, v64
	v_mov_b32_e32 v67, v64
	v_mov_b32_e32 v68, v64
	v_mov_b32_e32 v69, v64
	v_mov_b32_e32 v70, v64
	v_mov_b32_e32 v71, v64
	v_mov_b32_e32 v72, v64
	v_mov_b32_e32 v73, v64
	v_mov_b32_e32 v74, v64
	v_mov_b32_e32 v75, v64
	v_mov_b32_e32 v76, v64
	v_mov_b32_e32 v77, v64
	v_mov_b32_e32 v78, v64
	v_mov_b32_e32 v79, v64
	v_pk_mul_f32 v[30:31], v[30:31], v[8:9] op_sel_hi:[1,0]
	v_pk_mul_f32 v[28:29], v[28:29], v[8:9] op_sel_hi:[1,0]
	v_pk_mul_f32 v[26:27], v[26:27], v[8:9] op_sel_hi:[1,0]
	v_pk_mul_f32 v[24:25], v[24:25], v[8:9] op_sel_hi:[1,0]
	v_pk_mul_f32 v[22:23], v[22:23], v[8:9] op_sel_hi:[1,0]
	v_pk_mul_f32 v[20:21], v[20:21], v[8:9] op_sel_hi:[1,0]
	v_pk_mul_f32 v[18:19], v[18:19], v[8:9] op_sel_hi:[1,0]
	v_pk_mul_f32 v[16:17], v[16:17], v[8:9] op_sel_hi:[1,0]
	v_pk_mul_f32 v[46:47], v[46:47], v[8:9] op_sel_hi:[1,0]
	v_pk_mul_f32 v[44:45], v[44:45], v[8:9] op_sel_hi:[1,0]
	v_pk_mul_f32 v[42:43], v[42:43], v[8:9] op_sel_hi:[1,0]
	v_pk_mul_f32 v[40:41], v[40:41], v[8:9] op_sel_hi:[1,0]
	v_pk_mul_f32 v[38:39], v[38:39], v[8:9] op_sel_hi:[1,0]
	v_pk_mul_f32 v[36:37], v[36:37], v[8:9] op_sel_hi:[1,0]
	v_pk_mul_f32 v[34:35], v[34:35], v[8:9] op_sel_hi:[1,0]
	v_pk_mul_f32 v[32:33], v[32:33], v[8:9] op_sel_hi:[1,0]
	v_pk_mul_f32 v[62:63], v[62:63], v[8:9] op_sel_hi:[1,0]
	v_pk_mul_f32 v[60:61], v[60:61], v[8:9] op_sel_hi:[1,0]
	v_pk_mul_f32 v[58:59], v[58:59], v[8:9] op_sel_hi:[1,0]
	v_pk_mul_f32 v[56:57], v[56:57], v[8:9] op_sel_hi:[1,0]
	v_pk_mul_f32 v[54:55], v[54:55], v[8:9] op_sel_hi:[1,0]
	v_pk_mul_f32 v[52:53], v[52:53], v[8:9] op_sel_hi:[1,0]
	v_pk_mul_f32 v[50:51], v[50:51], v[8:9] op_sel_hi:[1,0]
	v_pk_mul_f32 v[48:49], v[48:49], v[8:9] op_sel_hi:[1,0]
	s_or_b64 s[20:21], s[4:5], s[0:1]
